# attention softmax-reference block: batch the six gain loads, DPP max reductions instead of serialized ds_bpermute
# speedup vs baseline: 1.0048x; 1.0014x over previous
; #define LAS __attribute__((address_space(3)))
; __global__ void __launch_bounds__(512) hymba_fwd(Args a) {
;     ...
;             { const int lane = threadIdx.x & 63;
;               float xq = fabsf(a.mqn[l * 64 + lane]), xk = fabsf(a.mkn[l * 64 + lane]);
;               float yq = fmaxf(fabsf(a.memqn[l * 128 + lane]), fabsf(a.memqn[l * 128 + 64 + lane])), yk = fmaxf(fabsf(a.memkn[l * 128 + lane]), fabsf(a.memkn[l * 128 + 64 + lane]));
; #pragma unroll
;               for (int ofs = 1; ofs < 64; ofs <<= 1) { xq = fmaxf(xq, __shfl_xor(xq, ofs)); xk = fmaxf(xk, __shfl_xor(xk, ofs)); yq = fmaxf(yq, __shfl_xor(yq, ofs)); yk = fmaxf(yk, __shfl_xor(yk, ofs)); }
;               if (threadIdx.x == 0) { ((LAS float*)(lds + 80000))[0] = xq * xk * (8.f * 1.03f * LOG2E); ((LAS float*)(lds + 80000))[1] = yq * yk * (11.3137085f * 1.03f * LOG2E); }
;               __syncthreads(); }
.LBB0_513:
	s_andn2_b64 vcc, exec, s[14:15]
	v_and_b32_e32 v192, 64, v188
	v_xor_b32_e32 v193, 16, v188
	v_xor_b32_e32 v194, 32, v188
	s_cbranch_vccnz .LBB0_634
	v_readlane_b32 s4, v244, 61
	s_lshl_b32 s42, s4, 7
	s_nop 0
	v_lshl_or_b32 v144, s4, 6, v185
	v_lshlrev_b64 v[0:1], 2, v[144:145]
	v_lshl_add_u64 v[2:3], s[92:93], 0, v[0:1]
	v_lshl_add_u64 v[0:1], s[94:95], 0, v[0:1]
	v_or_b32_e32 v144, s42, v185
	global_load_dword v6, v[0:1], off
	v_lshlrev_b64 v[0:1], 2, v[144:145]
	global_load_dword v4, v[2:3], off
	v_lshl_add_u64 v[2:3], s[72:73], 0, v[0:1]
	v_lshl_add_u64 v[0:1], s[74:75], 0, v[0:1]
	global_load_dword v5, v[2:3], off
	global_load_dword v7, v[2:3], off offset:256
	global_load_dword v12, v[0:1], off
	global_load_dword v13, v[0:1], off offset:256
	v_add_u32_e32 v8, 64, v192
	v_xor_b32_e32 v14, 1, v188
	v_xor_b32_e32 v15, 2, v188
	v_cmp_lt_i32_e32 vcc, v14, v8
	v_xor_b32_e32 v16, 4, v188
	v_xor_b32_e32 v17, 8, v188
	v_cndmask_b32_e32 v14, v188, v14, vcc
	v_cmp_lt_i32_e32 vcc, v15, v8
	v_lshlrev_b32_e32 v171, 2, v14
	s_nop 0
	v_cndmask_b32_e32 v15, v188, v15, vcc
	v_cmp_lt_i32_e32 vcc, v16, v8
	v_lshlrev_b32_e32 v195, 2, v15
	s_nop 0
	v_cndmask_b32_e32 v16, v188, v16, vcc
	v_cmp_lt_i32_e32 vcc, v17, v8
	v_lshlrev_b32_e32 v196, 2, v16
	s_nop 0
	v_cndmask_b32_e32 v17, v188, v17, vcc
	v_cmp_lt_i32_e32 vcc, v193, v8
	v_lshlrev_b32_e32 v197, 2, v17
	s_nop 0
	v_cndmask_b32_e32 v14, v188, v193, vcc
	v_cmp_lt_i32_e32 vcc, v194, v8
	v_lshlrev_b32_e32 v198, 2, v14
	s_nop 0
	v_cndmask_b32_e32 v15, v188, v194, vcc
	v_lshlrev_b32_e32 v199, 2, v15
	s_waitcnt vmcnt(0)
	v_max_f32_e64 v1, |v4|, |v4|
	v_max_f32_e64 v3, |v6|, |v6|
	v_max_f32_e64 v2, |v5|, |v5|
	v_max_f32_e64 v7, |v7|, |v7|
	v_max_f32_e64 v0, |v12|, |v12|
	v_max_f32_e64 v13, |v13|, |v13|
	v_max_f32_e32 v2, v2, v7
	v_max_f32_e32 v0, v0, v13
	s_nop 1
	v_max_f32_dpp v1, v1, v1 quad_perm:[1,0,3,2] row_mask:0xf bank_mask:0xf
	v_max_f32_dpp v3, v3, v3 quad_perm:[1,0,3,2] row_mask:0xf bank_mask:0xf
	v_max_f32_dpp v2, v2, v2 quad_perm:[1,0,3,2] row_mask:0xf bank_mask:0xf
	v_max_f32_dpp v0, v0, v0 quad_perm:[1,0,3,2] row_mask:0xf bank_mask:0xf
	v_max_f32_dpp v1, v1, v1 quad_perm:[2,3,0,1] row_mask:0xf bank_mask:0xf
	v_max_f32_dpp v3, v3, v3 quad_perm:[2,3,0,1] row_mask:0xf bank_mask:0xf
	v_max_f32_dpp v2, v2, v2 quad_perm:[2,3,0,1] row_mask:0xf bank_mask:0xf
	v_max_f32_dpp v0, v0, v0 quad_perm:[2,3,0,1] row_mask:0xf bank_mask:0xf
	v_max_f32_dpp v1, v1, v1 row_half_mirror row_mask:0xf bank_mask:0xf
	v_max_f32_dpp v3, v3, v3 row_half_mirror row_mask:0xf bank_mask:0xf
	v_max_f32_dpp v2, v2, v2 row_half_mirror row_mask:0xf bank_mask:0xf
	v_max_f32_dpp v0, v0, v0 row_half_mirror row_mask:0xf bank_mask:0xf
	v_max_f32_dpp v1, v1, v1 row_mirror row_mask:0xf bank_mask:0xf
	v_max_f32_dpp v3, v3, v3 row_mirror row_mask:0xf bank_mask:0xf
	v_max_f32_dpp v2, v2, v2 row_mirror row_mask:0xf bank_mask:0xf
	v_max_f32_dpp v0, v0, v0 row_mirror row_mask:0xf bank_mask:0xf
	v_max_f32_dpp v1, v1, v1 row_bcast:15 row_mask:0xa bank_mask:0xf
	v_max_f32_dpp v3, v3, v3 row_bcast:15 row_mask:0xa bank_mask:0xf
	v_max_f32_dpp v2, v2, v2 row_bcast:15 row_mask:0xa bank_mask:0xf
	v_max_f32_dpp v0, v0, v0 row_bcast:15 row_mask:0xa bank_mask:0xf
	v_max_f32_dpp v1, v1, v1 row_bcast:31 row_mask:0xc bank_mask:0xf
	v_max_f32_dpp v3, v3, v3 row_bcast:31 row_mask:0xc bank_mask:0xf
	v_max_f32_dpp v2, v2, v2 row_bcast:31 row_mask:0xc bank_mask:0xf
	v_max_f32_dpp v0, v0, v0 row_bcast:31 row_mask:0xc bank_mask:0xf
	s_nop 1
	v_readlane_b32 s4, v1, 63
	v_readlane_b32 s5, v3, 63
	v_readlane_b32 s8, v2, 63
	v_readlane_b32 s9, v0, 63
	s_mov_b64 s[14:15], exec
	v_readlane_b32 s10, v244, 6
	v_readlane_b32 s11, v244, 7
	s_and_b64 s[10:11], s[14:15], s[10:11]
	s_mov_b64 exec, s[10:11]
	s_cbranch_execz .LBB0_516
	v_mov_b32_e32 v2, s4
	v_mov_b32_e32 v3, s8
	v_mov_b32_e32 v6, s5
	v_mov_b32_e32 v7, s9
	s_mov_b32 s4, 0x413e3475
	s_mov_b32 s5, 0x41867ec4
	v_pk_mul_f32 v[0:1], v[2:3], v[6:7]
	s_nop 0
	v_pk_mul_f32 v[0:1], v[0:1], s[4:5]
	v_readlane_b32 s4, v244, 51
	s_nop 1
	v_mov_b32_e32 v2, s4
	ds_write_b64 v2, v[0:1]
